# v33 + grid barrier: the L1 invalidate is issued before the wait on the generation flag (overlaps the spin) instead of after it
# speedup vs baseline: 1.0360x; 1.0360x over previous
; __device__ __forceinline__ unsigned xb_ld(unsigned* p)              { return __hip_atomic_load(p, __ATOMIC_RELAXED, __HIP_MEMORY_SCOPE_AGENT); }
; __device__ __forceinline__ unsigned xb_add(unsigned* p, unsigned v) { return __hip_atomic_fetch_add(p, v, __ATOMIC_RELAXED, __HIP_MEMORY_SCOPE_AGENT); }
; #define XB_SPIN(cond, bar) do { unsigned _sp = 0; while (cond) { __builtin_amdgcn_s_sleep(1); \
;     if ((++_sp & 255u) == 0u) { if (xb_ld(&(bar)[XB_TMO])) break; if (_sp > XB_SPIN_CAP) { atomicAdd(&(bar)[XB_TMO], 1u); break; } } } } while (0)
; __device__ __forceinline__ void xcd_barrier(const XcdBarrier& b) {
;     ...
;         const unsigned old = xb_add(&bar[XB_XSUB(b.x)], 1u);
;         const unsigned gen = old / nloc;
;         if (old + 1u == (gen + 1u) * nloc) {
;             __builtin_amdgcn_fence(__ATOMIC_RELEASE, "agent");
;             asm volatile("s_waitcnt vmcnt(0)" ::: "memory");
;             const unsigned og = xb_add(&bar[XB_TOP], 1u);
;             const unsigned tg = og / nx;
;             if (og + 1u == (tg + 1u) * nx) xb_add(&bar[XB_TOPGEN], 1u);
;             else XB_SPIN(xb_ld(&bar[XB_TOPGEN]) == tg, bar);
;             __builtin_amdgcn_fence(__ATOMIC_ACQUIRE, "agent");
;             xb_add(&bar[XB_XGEN(b.x)], 1u);
;             asm volatile("s_waitcnt vmcnt(0)" ::: "memory");
;         } else {
;             XB_SPIN(xb_ld(&bar[XB_XGEN(b.x)]) == gen, bar);
.LBB0_569:
	s_or_b64 exec, exec, s[12:13]
	v_cvt_f32_u32_e32 v5, v3
	s_waitcnt vmcnt(0)
	v_readfirstlane_b32 s0, v4
	v_sub_u32_e32 v4, 0, v3
	v_rcp_iflag_f32_e32 v5, v5
	v_add_u32_e32 v6, s0, v1
	v_mul_f32_e32 v5, 0x4f7ffffe, v5
	v_cvt_u32_f32_e32 v5, v5
	v_mul_lo_u32 v1, v4, v5
	v_mul_hi_u32 v1, v5, v1
	v_add_u32_e32 v1, v5, v1
	v_mul_hi_u32 v1, v6, v1
	v_mul_lo_u32 v4, v1, v3
	v_sub_u32_e32 v4, v6, v4
	v_add_u32_e32 v5, 1, v1
	v_cmp_ge_u32_e32 vcc, v4, v3
	s_nop 1
	v_cndmask_b32_e32 v1, v1, v5, vcc
	v_sub_u32_e32 v5, v4, v3
	v_cndmask_b32_e32 v4, v4, v5, vcc
	v_add_u32_e32 v5, 1, v1
	v_cmp_ge_u32_e32 vcc, v4, v3
	v_add_u32_e32 v4, 1, v6
	s_nop 0
	v_cndmask_b32_e32 v1, v1, v5, vcc
	v_mul_lo_u32 v5, v3, v1
	v_add_u32_e32 v3, v5, v3
	v_cmp_ne_u32_e32 vcc, v4, v3
	s_and_saveexec_b64 s[0:1], vcc
	s_xor_b64 s[8:9], exec, s[0:1]
	s_cbranch_execz .LBB0_583
	s_waitcnt lgkmcnt(0)
	buffer_inv sc1
	v_mov_b32_e32 v2, 0x2000
	global_load_dword v2, v2, s[6:7] offset:1024 sc1
	s_add_u32 s14, s6, 0x2400
	s_addc_u32 s15, s7, 0
	s_waitcnt vmcnt(0)
	v_cmp_eq_u32_e32 vcc, v2, v1
	s_and_saveexec_b64 s[12:13], vcc
	s_cbranch_execz .LBB0_582
	s_mov_b32 s0, 1
	s_mov_b64 s[16:17], 0
	s_branch .LBB0_573

; __device__ __forceinline__ unsigned xb_ld(unsigned* p)              { return __hip_atomic_load(p, __ATOMIC_RELAXED, __HIP_MEMORY_SCOPE_AGENT); }
; __device__ __forceinline__ unsigned xb_add(unsigned* p, unsigned v) { return __hip_atomic_fetch_add(p, v, __ATOMIC_RELAXED, __HIP_MEMORY_SCOPE_AGENT); }
; #define XB_SPIN(cond, bar) do { unsigned _sp = 0; while (cond) { __builtin_amdgcn_s_sleep(1); \
;     if ((++_sp & 255u) == 0u) { if (xb_ld(&(bar)[XB_TMO])) break; if (_sp > XB_SPIN_CAP) { atomicAdd(&(bar)[XB_TMO], 1u); break; } } } } while (0)
; __device__ __forceinline__ void xcd_barrier(const XcdBarrier& b) {
;     ...
;         if (old + 1u == (gen + 1u) * nloc) {
;             __builtin_amdgcn_fence(__ATOMIC_RELEASE, "agent");
;             asm volatile("s_waitcnt vmcnt(0)" ::: "memory");
;             const unsigned og = xb_add(&bar[XB_TOP], 1u);
;             const unsigned tg = og / nx;
;             if (og + 1u == (tg + 1u) * nx) xb_add(&bar[XB_TOPGEN], 1u);
;             else XB_SPIN(xb_ld(&bar[XB_TOPGEN]) == tg, bar);
;             __builtin_amdgcn_fence(__ATOMIC_ACQUIRE, "agent");
;             xb_add(&bar[XB_XGEN(b.x)], 1u);
;             asm volatile("s_waitcnt vmcnt(0)" ::: "memory");
;         } else {
;             XB_SPIN(xb_ld(&bar[XB_XGEN(b.x)]) == gen, bar);
;             __builtin_amdgcn_fence(__ATOMIC_ACQUIRE, "agent");
;             asm volatile("s_waitcnt vmcnt(0)" ::: "memory");
.LBB0_582:
	s_or_b64 exec, exec, s[12:13]
	s_waitcnt vmcnt(0)
	s_nop 0
	s_waitcnt vmcnt(0)
.LBB0_583:
	s_andn2_saveexec_b64 s[0:1], s[8:9]
	s_cbranch_execz .LBB0_603
	s_mov_b64 s[8:9], exec
	buffer_wbl2 sc1
	s_waitcnt lgkmcnt(0)
	s_waitcnt vmcnt(0)
	buffer_inv sc1
	v_mbcnt_lo_u32_b32 v1, s8, 0
	v_mbcnt_hi_u32_b32 v1, s9, v1
	v_cmp_eq_u32_e32 vcc, 0, v1
	s_and_saveexec_b64 s[12:13], vcc
	s_cbranch_execz .LBB0_586
	s_bcnt1_i32_b64 s0, s[8:9]
	v_mov_b32_e32 v3, s0
	v_readlane_b32 s0, v254, 29
	v_readlane_b32 s1, v254, 30
	s_nop 4
	global_atomic_add v3, v0, v3, s[0:1] sc0

; __device__ __forceinline__ unsigned xb_ld(unsigned* p)              { return __hip_atomic_load(p, __ATOMIC_RELAXED, __HIP_MEMORY_SCOPE_AGENT); }
; __device__ __forceinline__ unsigned xb_add(unsigned* p, unsigned v) { return __hip_atomic_fetch_add(p, v, __ATOMIC_RELAXED, __HIP_MEMORY_SCOPE_AGENT); }
; #define XB_SPIN(cond, bar) do { unsigned _sp = 0; while (cond) { __builtin_amdgcn_s_sleep(1); \
;     if ((++_sp & 255u) == 0u) { if (xb_ld(&(bar)[XB_TMO])) break; if (_sp > XB_SPIN_CAP) { atomicAdd(&(bar)[XB_TMO], 1u); break; } } } } while (0)
; __device__ __forceinline__ void xcd_barrier(const XcdBarrier& b) {
;     ...
;             if (og + 1u == (tg + 1u) * nx) xb_add(&bar[XB_TOPGEN], 1u);
;             else XB_SPIN(xb_ld(&bar[XB_TOPGEN]) == tg, bar);
;             __builtin_amdgcn_fence(__ATOMIC_ACQUIRE, "agent");
;             xb_add(&bar[XB_XGEN(b.x)], 1u);
.LBB0_600:
	s_or_b64 exec, exec, s[8:9]
	s_mov_b64 s[8:9], exec
	v_mbcnt_lo_u32_b32 v1, s8, 0
	v_mbcnt_hi_u32_b32 v1, s9, v1
	v_cmp_eq_u32_e32 vcc, 0, v1
	s_waitcnt vmcnt(0)
	s_nop 0
	s_and_saveexec_b64 s[12:13], vcc
	s_cbranch_execz .LBB0_602
	s_bcnt1_i32_b64 s0, s[8:9]
	v_mov_b32_e32 v1, s0
	v_mov_b32_e32 v2, 0x2000
	global_atomic_add v2, v1, s[6:7] offset:1024

; __device__ __forceinline__ unsigned xb_ld(unsigned* p)              { return __hip_atomic_load(p, __ATOMIC_RELAXED, __HIP_MEMORY_SCOPE_AGENT); }
; __device__ __forceinline__ unsigned xb_add(unsigned* p, unsigned v) { return __hip_atomic_fetch_add(p, v, __ATOMIC_RELAXED, __HIP_MEMORY_SCOPE_AGENT); }
; #define XB_SPIN(cond, bar) do { unsigned _sp = 0; while (cond) { __builtin_amdgcn_s_sleep(1); \
;     if ((++_sp & 255u) == 0u) { if (xb_ld(&(bar)[XB_TMO])) break; if (_sp > XB_SPIN_CAP) { atomicAdd(&(bar)[XB_TMO], 1u); break; } } } } while (0)
; __device__ __forceinline__ void xcd_barrier(const XcdBarrier& b) {
;     ...
;         const unsigned old = xb_add(&bar[XB_XSUB(b.x)], 1u);
;         const unsigned gen = old / nloc;
;         if (old + 1u == (gen + 1u) * nloc) {
;             __builtin_amdgcn_fence(__ATOMIC_RELEASE, "agent");
;             asm volatile("s_waitcnt vmcnt(0)" ::: "memory");
;             const unsigned og = xb_add(&bar[XB_TOP], 1u);
;             const unsigned tg = og / nx;
;             if (og + 1u == (tg + 1u) * nx) xb_add(&bar[XB_TOPGEN], 1u);
;             else XB_SPIN(xb_ld(&bar[XB_TOPGEN]) == tg, bar);
;             __builtin_amdgcn_fence(__ATOMIC_ACQUIRE, "agent");
;             xb_add(&bar[XB_XGEN(b.x)], 1u);
;             asm volatile("s_waitcnt vmcnt(0)" ::: "memory");
;         } else {
;             XB_SPIN(xb_ld(&bar[XB_XGEN(b.x)]) == gen, bar);
.LBB0_630:
	s_or_b64 exec, exec, s[14:15]
	v_cvt_f32_u32_e32 v5, v3
	s_waitcnt vmcnt(0)
	v_readfirstlane_b32 s0, v4
	v_sub_u32_e32 v4, 0, v3
	v_rcp_iflag_f32_e32 v5, v5
	v_add_u32_e32 v6, s0, v1
	v_mul_f32_e32 v5, 0x4f7ffffe, v5
	v_cvt_u32_f32_e32 v5, v5
	v_mul_lo_u32 v1, v4, v5
	v_mul_hi_u32 v1, v5, v1
	v_add_u32_e32 v1, v5, v1
	v_mul_hi_u32 v1, v6, v1
	v_mul_lo_u32 v4, v1, v3
	v_sub_u32_e32 v4, v6, v4
	v_add_u32_e32 v5, 1, v1
	v_cmp_ge_u32_e32 vcc, v4, v3
	s_nop 1
	v_cndmask_b32_e32 v1, v1, v5, vcc
	v_sub_u32_e32 v5, v4, v3
	v_cndmask_b32_e32 v4, v4, v5, vcc
	v_add_u32_e32 v5, 1, v1
	v_cmp_ge_u32_e32 vcc, v4, v3
	v_add_u32_e32 v4, 1, v6
	s_nop 0
	v_cndmask_b32_e32 v1, v1, v5, vcc
	v_mul_lo_u32 v5, v3, v1
	v_add_u32_e32 v3, v5, v3
	v_cmp_ne_u32_e32 vcc, v4, v3
	s_and_saveexec_b64 s[0:1], vcc
	s_xor_b64 s[12:13], exec, s[0:1]
	s_cbranch_execz .LBB0_644
	s_waitcnt lgkmcnt(0)
	buffer_inv sc1
	v_mov_b32_e32 v2, 0x2000
	global_load_dword v2, v2, s[6:7] offset:1024 sc1
	s_add_u32 s16, s6, 0x2400
	s_addc_u32 s17, s7, 0
	s_waitcnt vmcnt(0)
	v_cmp_eq_u32_e32 vcc, v2, v1
	s_and_saveexec_b64 s[14:15], vcc
	s_cbranch_execz .LBB0_643
	s_mov_b32 s0, 1
	s_mov_b64 s[18:19], 0
	s_branch .LBB0_634

; __device__ __forceinline__ unsigned xb_ld(unsigned* p)              { return __hip_atomic_load(p, __ATOMIC_RELAXED, __HIP_MEMORY_SCOPE_AGENT); }
; __device__ __forceinline__ unsigned xb_add(unsigned* p, unsigned v) { return __hip_atomic_fetch_add(p, v, __ATOMIC_RELAXED, __HIP_MEMORY_SCOPE_AGENT); }
; #define XB_SPIN(cond, bar) do { unsigned _sp = 0; while (cond) { __builtin_amdgcn_s_sleep(1); \
;     if ((++_sp & 255u) == 0u) { if (xb_ld(&(bar)[XB_TMO])) break; if (_sp > XB_SPIN_CAP) { atomicAdd(&(bar)[XB_TMO], 1u); break; } } } } while (0)
; __device__ __forceinline__ void xcd_barrier(const XcdBarrier& b) {
;     ...
;         if (old + 1u == (gen + 1u) * nloc) {
;             __builtin_amdgcn_fence(__ATOMIC_RELEASE, "agent");
;             asm volatile("s_waitcnt vmcnt(0)" ::: "memory");
;             const unsigned og = xb_add(&bar[XB_TOP], 1u);
;             const unsigned tg = og / nx;
;             if (og + 1u == (tg + 1u) * nx) xb_add(&bar[XB_TOPGEN], 1u);
;             else XB_SPIN(xb_ld(&bar[XB_TOPGEN]) == tg, bar);
;             __builtin_amdgcn_fence(__ATOMIC_ACQUIRE, "agent");
;             xb_add(&bar[XB_XGEN(b.x)], 1u);
;             asm volatile("s_waitcnt vmcnt(0)" ::: "memory");
;         } else {
;             XB_SPIN(xb_ld(&bar[XB_XGEN(b.x)]) == gen, bar);
;             __builtin_amdgcn_fence(__ATOMIC_ACQUIRE, "agent");
;             asm volatile("s_waitcnt vmcnt(0)" ::: "memory");
.LBB0_643:
	s_or_b64 exec, exec, s[14:15]
	s_waitcnt vmcnt(0)
	s_nop 0
	s_waitcnt vmcnt(0)
.LBB0_644:
	s_andn2_saveexec_b64 s[0:1], s[12:13]
	s_cbranch_execz .LBB0_664
	s_mov_b64 s[12:13], exec
	buffer_wbl2 sc1
	s_waitcnt lgkmcnt(0)
	s_waitcnt vmcnt(0)
	buffer_inv sc1
	v_mbcnt_lo_u32_b32 v1, s12, 0
	v_mbcnt_hi_u32_b32 v1, s13, v1
	v_cmp_eq_u32_e32 vcc, 0, v1
	s_and_saveexec_b64 s[14:15], vcc
	s_cbranch_execz .LBB0_647
	s_bcnt1_i32_b64 s0, s[12:13]
	v_mov_b32_e32 v3, s0
	v_readlane_b32 s0, v254, 29
	v_readlane_b32 s1, v254, 30
	s_nop 4
	global_atomic_add v3, v0, v3, s[0:1] sc0

; __device__ __forceinline__ unsigned xb_ld(unsigned* p)              { return __hip_atomic_load(p, __ATOMIC_RELAXED, __HIP_MEMORY_SCOPE_AGENT); }
; __device__ __forceinline__ unsigned xb_add(unsigned* p, unsigned v) { return __hip_atomic_fetch_add(p, v, __ATOMIC_RELAXED, __HIP_MEMORY_SCOPE_AGENT); }
; #define XB_SPIN(cond, bar) do { unsigned _sp = 0; while (cond) { __builtin_amdgcn_s_sleep(1); \
;     if ((++_sp & 255u) == 0u) { if (xb_ld(&(bar)[XB_TMO])) break; if (_sp > XB_SPIN_CAP) { atomicAdd(&(bar)[XB_TMO], 1u); break; } } } } while (0)
; __device__ __forceinline__ void xcd_barrier(const XcdBarrier& b) {
;     ...
;             if (og + 1u == (tg + 1u) * nx) xb_add(&bar[XB_TOPGEN], 1u);
;             else XB_SPIN(xb_ld(&bar[XB_TOPGEN]) == tg, bar);
;             __builtin_amdgcn_fence(__ATOMIC_ACQUIRE, "agent");
;             xb_add(&bar[XB_XGEN(b.x)], 1u);
.LBB0_661:
	s_or_b64 exec, exec, s[12:13]
	s_mov_b64 s[12:13], exec
	v_mbcnt_lo_u32_b32 v1, s12, 0
	v_mbcnt_hi_u32_b32 v1, s13, v1
	v_cmp_eq_u32_e32 vcc, 0, v1
	s_waitcnt vmcnt(0)
	s_nop 0
	s_and_saveexec_b64 s[14:15], vcc
	s_cbranch_execz .LBB0_663
	s_bcnt1_i32_b64 s0, s[12:13]
	v_mov_b32_e32 v1, s0
	v_mov_b32_e32 v2, 0x2000
	global_atomic_add v2, v1, s[6:7] offset:1024

; __device__ __forceinline__ unsigned xb_ld(unsigned* p)              { return __hip_atomic_load(p, __ATOMIC_RELAXED, __HIP_MEMORY_SCOPE_AGENT); }
; __device__ __forceinline__ unsigned xb_add(unsigned* p, unsigned v) { return __hip_atomic_fetch_add(p, v, __ATOMIC_RELAXED, __HIP_MEMORY_SCOPE_AGENT); }
; #define XB_SPIN(cond, bar) do { unsigned _sp = 0; while (cond) { __builtin_amdgcn_s_sleep(1); \
;     if ((++_sp & 255u) == 0u) { if (xb_ld(&(bar)[XB_TMO])) break; if (_sp > XB_SPIN_CAP) { atomicAdd(&(bar)[XB_TMO], 1u); break; } } } } while (0)
; __device__ __forceinline__ void xcd_barrier(const XcdBarrier& b) {
;     ...
;         const unsigned old = xb_add(&bar[XB_XSUB(b.x)], 1u);
;         const unsigned gen = old / nloc;
;         if (old + 1u == (gen + 1u) * nloc) {
;             __builtin_amdgcn_fence(__ATOMIC_RELEASE, "agent");
;             asm volatile("s_waitcnt vmcnt(0)" ::: "memory");
;             const unsigned og = xb_add(&bar[XB_TOP], 1u);
;             const unsigned tg = og / nx;
;             if (og + 1u == (tg + 1u) * nx) xb_add(&bar[XB_TOPGEN], 1u);
;             else XB_SPIN(xb_ld(&bar[XB_TOPGEN]) == tg, bar);
;             __builtin_amdgcn_fence(__ATOMIC_ACQUIRE, "agent");
;             xb_add(&bar[XB_XGEN(b.x)], 1u);
;             asm volatile("s_waitcnt vmcnt(0)" ::: "memory");
;         } else {
;             XB_SPIN(xb_ld(&bar[XB_XGEN(b.x)]) == gen, bar);
.LBB0_828:
	s_or_b64 exec, exec, s[14:15]
	v_cvt_f32_u32_e32 v5, v3
	s_waitcnt vmcnt(0)
	v_readfirstlane_b32 s0, v4
	v_sub_u32_e32 v4, 0, v3
	v_rcp_iflag_f32_e32 v5, v5
	v_add_u32_e32 v6, s0, v1
	v_mul_f32_e32 v5, 0x4f7ffffe, v5
	v_cvt_u32_f32_e32 v5, v5
	v_mul_lo_u32 v1, v4, v5
	v_mul_hi_u32 v1, v5, v1
	v_add_u32_e32 v1, v5, v1
	v_mul_hi_u32 v1, v6, v1
	v_mul_lo_u32 v4, v1, v3
	v_sub_u32_e32 v4, v6, v4
	v_add_u32_e32 v5, 1, v1
	v_cmp_ge_u32_e32 vcc, v4, v3
	s_nop 1
	v_cndmask_b32_e32 v1, v1, v5, vcc
	v_sub_u32_e32 v5, v4, v3
	v_cndmask_b32_e32 v4, v4, v5, vcc
	v_add_u32_e32 v5, 1, v1
	v_cmp_ge_u32_e32 vcc, v4, v3
	v_add_u32_e32 v4, 1, v6
	s_nop 0
	v_cndmask_b32_e32 v1, v1, v5, vcc
	v_mul_lo_u32 v5, v3, v1
	v_add_u32_e32 v3, v5, v3
	v_cmp_ne_u32_e32 vcc, v4, v3
	s_and_saveexec_b64 s[0:1], vcc
	s_xor_b64 s[12:13], exec, s[0:1]
	s_cbranch_execz .LBB0_842
	s_waitcnt lgkmcnt(0)
	buffer_inv sc1
	v_mov_b32_e32 v2, 0x2000
	global_load_dword v2, v2, s[8:9] offset:1024 sc1
	s_add_u32 s16, s8, 0x2400
	s_addc_u32 s17, s9, 0
	s_waitcnt vmcnt(0)
	v_cmp_eq_u32_e32 vcc, v2, v1
	s_and_saveexec_b64 s[14:15], vcc
	s_cbranch_execz .LBB0_841
	s_mov_b32 s0, 1
	s_mov_b64 s[18:19], 0
	s_branch .LBB0_832

; __device__ __forceinline__ unsigned xb_ld(unsigned* p)              { return __hip_atomic_load(p, __ATOMIC_RELAXED, __HIP_MEMORY_SCOPE_AGENT); }
; __device__ __forceinline__ unsigned xb_add(unsigned* p, unsigned v) { return __hip_atomic_fetch_add(p, v, __ATOMIC_RELAXED, __HIP_MEMORY_SCOPE_AGENT); }
; #define XB_SPIN(cond, bar) do { unsigned _sp = 0; while (cond) { __builtin_amdgcn_s_sleep(1); \
;     if ((++_sp & 255u) == 0u) { if (xb_ld(&(bar)[XB_TMO])) break; if (_sp > XB_SPIN_CAP) { atomicAdd(&(bar)[XB_TMO], 1u); break; } } } } while (0)
; __device__ __forceinline__ void xcd_barrier(const XcdBarrier& b) {
;     ...
;             if (og + 1u == (tg + 1u) * nx) xb_add(&bar[XB_TOPGEN], 1u);
;             else XB_SPIN(xb_ld(&bar[XB_TOPGEN]) == tg, bar);
;             __builtin_amdgcn_fence(__ATOMIC_ACQUIRE, "agent");
;             xb_add(&bar[XB_XGEN(b.x)], 1u);
.LBB0_859:
	s_or_b64 exec, exec, s[12:13]
	s_mov_b64 s[12:13], exec
	v_mbcnt_lo_u32_b32 v1, s12, 0
	v_mbcnt_hi_u32_b32 v1, s13, v1
	v_cmp_eq_u32_e32 vcc, 0, v1
	s_waitcnt vmcnt(0)
	s_nop 0
	s_and_saveexec_b64 s[14:15], vcc
	s_cbranch_execz .LBB0_861
	s_bcnt1_i32_b64 s0, s[12:13]
	v_mov_b32_e32 v1, s0
	v_mov_b32_e32 v2, 0x2000
	global_atomic_add v2, v1, s[8:9] offset:1024

; __device__ __forceinline__ unsigned xb_ld(unsigned* p)              { return __hip_atomic_load(p, __ATOMIC_RELAXED, __HIP_MEMORY_SCOPE_AGENT); }
; __device__ __forceinline__ unsigned xb_add(unsigned* p, unsigned v) { return __hip_atomic_fetch_add(p, v, __ATOMIC_RELAXED, __HIP_MEMORY_SCOPE_AGENT); }
; #define XB_SPIN(cond, bar) do { unsigned _sp = 0; while (cond) { __builtin_amdgcn_s_sleep(1); \
;     if ((++_sp & 255u) == 0u) { if (xb_ld(&(bar)[XB_TMO])) break; if (_sp > XB_SPIN_CAP) { atomicAdd(&(bar)[XB_TMO], 1u); break; } } } } while (0)
; __device__ __forceinline__ void xcd_barrier(const XcdBarrier& b) {
;     ...
;         const unsigned old = xb_add(&bar[XB_XSUB(b.x)], 1u);
;         const unsigned gen = old / nloc;
;         if (old + 1u == (gen + 1u) * nloc) {
;             __builtin_amdgcn_fence(__ATOMIC_RELEASE, "agent");
;             asm volatile("s_waitcnt vmcnt(0)" ::: "memory");
;             const unsigned og = xb_add(&bar[XB_TOP], 1u);
;             const unsigned tg = og / nx;
;             if (og + 1u == (tg + 1u) * nx) xb_add(&bar[XB_TOPGEN], 1u);
;             else XB_SPIN(xb_ld(&bar[XB_TOPGEN]) == tg, bar);
;             __builtin_amdgcn_fence(__ATOMIC_ACQUIRE, "agent");
;             xb_add(&bar[XB_XGEN(b.x)], 1u);
;             asm volatile("s_waitcnt vmcnt(0)" ::: "memory");
;         } else {
;             XB_SPIN(xb_ld(&bar[XB_XGEN(b.x)]) == gen, bar);
.LBB0_1134:
	s_or_b64 exec, exec, s[10:11]
	v_cvt_f32_u32_e32 v5, v3
	s_waitcnt vmcnt(0)
	v_readfirstlane_b32 s0, v4
	v_sub_u32_e32 v4, 0, v3
	v_rcp_iflag_f32_e32 v5, v5
	v_add_u32_e32 v6, s0, v1
	v_mul_f32_e32 v5, 0x4f7ffffe, v5
	v_cvt_u32_f32_e32 v5, v5
	v_mul_lo_u32 v1, v4, v5
	v_mul_hi_u32 v1, v5, v1
	v_add_u32_e32 v1, v5, v1
	v_mul_hi_u32 v1, v6, v1
	v_mul_lo_u32 v4, v1, v3
	v_sub_u32_e32 v4, v6, v4
	v_add_u32_e32 v5, 1, v1
	v_cmp_ge_u32_e32 vcc, v4, v3
	s_nop 1
	v_cndmask_b32_e32 v1, v1, v5, vcc
	v_sub_u32_e32 v5, v4, v3
	v_cndmask_b32_e32 v4, v4, v5, vcc
	v_add_u32_e32 v5, 1, v1
	v_cmp_ge_u32_e32 vcc, v4, v3
	v_add_u32_e32 v4, 1, v6
	s_nop 0
	v_cndmask_b32_e32 v1, v1, v5, vcc
	v_mul_lo_u32 v5, v3, v1
	v_add_u32_e32 v3, v5, v3
	v_cmp_ne_u32_e32 vcc, v4, v3
	s_and_saveexec_b64 s[0:1], vcc
	s_xor_b64 s[8:9], exec, s[0:1]
	s_cbranch_execz .LBB0_1148
	s_waitcnt lgkmcnt(0)
	buffer_inv sc1
	v_mov_b32_e32 v2, 0x2000
	global_load_dword v2, v2, s[6:7] offset:1024 sc1
	s_add_u32 s12, s6, 0x2400
	s_addc_u32 s13, s7, 0
	s_waitcnt vmcnt(0)
	v_cmp_eq_u32_e32 vcc, v2, v1
	s_and_saveexec_b64 s[10:11], vcc
	s_cbranch_execz .LBB0_1147
	s_mov_b32 s0, 1
	s_mov_b64 s[14:15], 0
	s_branch .LBB0_1138

; __device__ __forceinline__ unsigned xb_ld(unsigned* p)              { return __hip_atomic_load(p, __ATOMIC_RELAXED, __HIP_MEMORY_SCOPE_AGENT); }
; __device__ __forceinline__ unsigned xb_add(unsigned* p, unsigned v) { return __hip_atomic_fetch_add(p, v, __ATOMIC_RELAXED, __HIP_MEMORY_SCOPE_AGENT); }
; #define XB_SPIN(cond, bar) do { unsigned _sp = 0; while (cond) { __builtin_amdgcn_s_sleep(1); \
;     if ((++_sp & 255u) == 0u) { if (xb_ld(&(bar)[XB_TMO])) break; if (_sp > XB_SPIN_CAP) { atomicAdd(&(bar)[XB_TMO], 1u); break; } } } } while (0)
; __device__ __forceinline__ void xcd_barrier(const XcdBarrier& b) {
;     ...
;         if (old + 1u == (gen + 1u) * nloc) {
;             __builtin_amdgcn_fence(__ATOMIC_RELEASE, "agent");
;             asm volatile("s_waitcnt vmcnt(0)" ::: "memory");
;             const unsigned og = xb_add(&bar[XB_TOP], 1u);
;             const unsigned tg = og / nx;
;             if (og + 1u == (tg + 1u) * nx) xb_add(&bar[XB_TOPGEN], 1u);
;             else XB_SPIN(xb_ld(&bar[XB_TOPGEN]) == tg, bar);
;             __builtin_amdgcn_fence(__ATOMIC_ACQUIRE, "agent");
;             xb_add(&bar[XB_XGEN(b.x)], 1u);
;             asm volatile("s_waitcnt vmcnt(0)" ::: "memory");
;         } else {
;             XB_SPIN(xb_ld(&bar[XB_XGEN(b.x)]) == gen, bar);
;             __builtin_amdgcn_fence(__ATOMIC_ACQUIRE, "agent");
;             asm volatile("s_waitcnt vmcnt(0)" ::: "memory");
.LBB0_1147:
	s_or_b64 exec, exec, s[10:11]
	s_waitcnt vmcnt(0)
	s_nop 0
	s_waitcnt vmcnt(0)
.LBB0_1148:
	s_andn2_saveexec_b64 s[0:1], s[8:9]
	s_cbranch_execz .LBB0_1168
	s_mov_b64 s[8:9], exec
	buffer_wbl2 sc1
	s_waitcnt lgkmcnt(0)
	s_waitcnt vmcnt(0)
	buffer_inv sc1
	v_mbcnt_lo_u32_b32 v1, s8, 0
	v_mbcnt_hi_u32_b32 v1, s9, v1
	v_cmp_eq_u32_e32 vcc, 0, v1
	s_and_saveexec_b64 s[10:11], vcc
	s_cbranch_execz .LBB0_1151
	s_bcnt1_i32_b64 s0, s[8:9]
	v_mov_b32_e32 v3, s0
	v_readlane_b32 s0, v254, 29
	v_readlane_b32 s1, v254, 30
	s_nop 4
	global_atomic_add v3, v0, v3, s[0:1] sc0

; __device__ __forceinline__ unsigned xb_ld(unsigned* p)              { return __hip_atomic_load(p, __ATOMIC_RELAXED, __HIP_MEMORY_SCOPE_AGENT); }
; __device__ __forceinline__ unsigned xb_add(unsigned* p, unsigned v) { return __hip_atomic_fetch_add(p, v, __ATOMIC_RELAXED, __HIP_MEMORY_SCOPE_AGENT); }
; #define XB_SPIN(cond, bar) do { unsigned _sp = 0; while (cond) { __builtin_amdgcn_s_sleep(1); \
;     if ((++_sp & 255u) == 0u) { if (xb_ld(&(bar)[XB_TMO])) break; if (_sp > XB_SPIN_CAP) { atomicAdd(&(bar)[XB_TMO], 1u); break; } } } } while (0)
; __device__ __forceinline__ void xcd_barrier(const XcdBarrier& b) {
;     ...
;             if (og + 1u == (tg + 1u) * nx) xb_add(&bar[XB_TOPGEN], 1u);
;             else XB_SPIN(xb_ld(&bar[XB_TOPGEN]) == tg, bar);
;             __builtin_amdgcn_fence(__ATOMIC_ACQUIRE, "agent");
;             xb_add(&bar[XB_XGEN(b.x)], 1u);
.LBB0_1165:
	s_or_b64 exec, exec, s[8:9]
	s_mov_b64 s[8:9], exec
	v_mbcnt_lo_u32_b32 v1, s8, 0
	v_mbcnt_hi_u32_b32 v1, s9, v1
	v_cmp_eq_u32_e32 vcc, 0, v1
	s_waitcnt vmcnt(0)
	s_nop 0
	s_and_saveexec_b64 s[10:11], vcc
	s_cbranch_execz .LBB0_1167
	s_bcnt1_i32_b64 s0, s[8:9]
	v_mov_b32_e32 v1, s0
	v_mov_b32_e32 v2, 0x2000
	global_atomic_add v2, v1, s[6:7] offset:1024

; __device__ __forceinline__ unsigned xb_ld(unsigned* p)              { return __hip_atomic_load(p, __ATOMIC_RELAXED, __HIP_MEMORY_SCOPE_AGENT); }
; __device__ __forceinline__ unsigned xb_add(unsigned* p, unsigned v) { return __hip_atomic_fetch_add(p, v, __ATOMIC_RELAXED, __HIP_MEMORY_SCOPE_AGENT); }
; #define XB_SPIN(cond, bar) do { unsigned _sp = 0; while (cond) { __builtin_amdgcn_s_sleep(1); \
;     if ((++_sp & 255u) == 0u) { if (xb_ld(&(bar)[XB_TMO])) break; if (_sp > XB_SPIN_CAP) { atomicAdd(&(bar)[XB_TMO], 1u); break; } } } } while (0)
; __device__ __forceinline__ void xcd_barrier(const XcdBarrier& b) {
;     ...
;         const unsigned old = xb_add(&bar[XB_XSUB(b.x)], 1u);
;         const unsigned gen = old / nloc;
;         if (old + 1u == (gen + 1u) * nloc) {
;             __builtin_amdgcn_fence(__ATOMIC_RELEASE, "agent");
;             asm volatile("s_waitcnt vmcnt(0)" ::: "memory");
;             const unsigned og = xb_add(&bar[XB_TOP], 1u);
;             const unsigned tg = og / nx;
;             if (og + 1u == (tg + 1u) * nx) xb_add(&bar[XB_TOPGEN], 1u);
;             else XB_SPIN(xb_ld(&bar[XB_TOPGEN]) == tg, bar);
;             __builtin_amdgcn_fence(__ATOMIC_ACQUIRE, "agent");
;             xb_add(&bar[XB_XGEN(b.x)], 1u);
;             asm volatile("s_waitcnt vmcnt(0)" ::: "memory");
;         } else {
;             XB_SPIN(xb_ld(&bar[XB_XGEN(b.x)]) == gen, bar);
.LBB0_2078:
	s_or_b64 exec, exec, s[8:9]
	v_cvt_f32_u32_e32 v5, v3
	s_waitcnt vmcnt(0)
	v_readfirstlane_b32 s3, v4
	v_sub_u32_e32 v4, 0, v3
	v_rcp_iflag_f32_e32 v5, v5
	v_add_u32_e32 v6, s3, v1
	v_mul_f32_e32 v5, 0x4f7ffffe, v5
	v_cvt_u32_f32_e32 v5, v5
	v_mul_lo_u32 v1, v4, v5
	v_mul_hi_u32 v1, v5, v1
	v_add_u32_e32 v1, v5, v1
	v_mul_hi_u32 v1, v6, v1
	v_mul_lo_u32 v4, v1, v3
	v_sub_u32_e32 v4, v6, v4
	v_add_u32_e32 v5, 1, v1
	v_cmp_ge_u32_e32 vcc, v4, v3
	s_nop 1
	v_cndmask_b32_e32 v1, v1, v5, vcc
	v_sub_u32_e32 v5, v4, v3
	v_cndmask_b32_e32 v4, v4, v5, vcc
	v_add_u32_e32 v5, 1, v1
	v_cmp_ge_u32_e32 vcc, v4, v3
	v_add_u32_e32 v4, 1, v6
	s_nop 0
	v_cndmask_b32_e32 v1, v1, v5, vcc
	v_mul_lo_u32 v5, v3, v1
	v_add_u32_e32 v3, v5, v3
	v_cmp_ne_u32_e32 vcc, v4, v3
	s_and_saveexec_b64 s[6:7], vcc
	s_xor_b64 s[6:7], exec, s[6:7]
	s_cbranch_execz .LBB0_2092
	s_waitcnt lgkmcnt(0)
	buffer_inv sc1
	v_mov_b32_e32 v2, 0x2000
	global_load_dword v2, v2, s[4:5] offset:1024 sc1
	s_add_u32 s10, s4, 0x2400
	s_addc_u32 s11, s5, 0
	s_waitcnt vmcnt(0)
	v_cmp_eq_u32_e32 vcc, v2, v1
	s_and_saveexec_b64 s[8:9], vcc
	s_cbranch_execz .LBB0_2091
	s_mov_b32 s3, 1
	s_mov_b64 s[12:13], 0
	s_branch .LBB0_2082

; __device__ __forceinline__ unsigned xb_ld(unsigned* p)              { return __hip_atomic_load(p, __ATOMIC_RELAXED, __HIP_MEMORY_SCOPE_AGENT); }
; __device__ __forceinline__ unsigned xb_add(unsigned* p, unsigned v) { return __hip_atomic_fetch_add(p, v, __ATOMIC_RELAXED, __HIP_MEMORY_SCOPE_AGENT); }
; #define XB_SPIN(cond, bar) do { unsigned _sp = 0; while (cond) { __builtin_amdgcn_s_sleep(1); \
;     if ((++_sp & 255u) == 0u) { if (xb_ld(&(bar)[XB_TMO])) break; if (_sp > XB_SPIN_CAP) { atomicAdd(&(bar)[XB_TMO], 1u); break; } } } } while (0)
; __device__ __forceinline__ void xcd_barrier(const XcdBarrier& b) {
;     ...
;         if (old + 1u == (gen + 1u) * nloc) {
;             __builtin_amdgcn_fence(__ATOMIC_RELEASE, "agent");
;             asm volatile("s_waitcnt vmcnt(0)" ::: "memory");
;             const unsigned og = xb_add(&bar[XB_TOP], 1u);
;             const unsigned tg = og / nx;
;             if (og + 1u == (tg + 1u) * nx) xb_add(&bar[XB_TOPGEN], 1u);
;             else XB_SPIN(xb_ld(&bar[XB_TOPGEN]) == tg, bar);
;             __builtin_amdgcn_fence(__ATOMIC_ACQUIRE, "agent");
;             xb_add(&bar[XB_XGEN(b.x)], 1u);
;             asm volatile("s_waitcnt vmcnt(0)" ::: "memory");
;         } else {
;             XB_SPIN(xb_ld(&bar[XB_XGEN(b.x)]) == gen, bar);
;             __builtin_amdgcn_fence(__ATOMIC_ACQUIRE, "agent");
;             asm volatile("s_waitcnt vmcnt(0)" ::: "memory");
.LBB0_2091:
	s_or_b64 exec, exec, s[8:9]
	s_waitcnt vmcnt(0)
	s_nop 0
	s_waitcnt vmcnt(0)
.LBB0_2092:
	s_andn2_saveexec_b64 s[6:7], s[6:7]
	s_cbranch_execz .LBB0_2112
	s_mov_b64 s[6:7], exec
	buffer_wbl2 sc1
	s_waitcnt lgkmcnt(0)
	s_waitcnt vmcnt(0)
	buffer_inv sc1
	v_mbcnt_lo_u32_b32 v1, s6, 0
	v_mbcnt_hi_u32_b32 v1, s7, v1
	v_cmp_eq_u32_e32 vcc, 0, v1
	s_and_saveexec_b64 s[8:9], vcc
	s_cbranch_execz .LBB0_2095
	s_bcnt1_i32_b64 s3, s[6:7]
	v_readlane_b32 s6, v254, 29
	v_mov_b32_e32 v3, s3
	v_readlane_b32 s7, v254, 30
	s_nop 4
	global_atomic_add v3, v0, v3, s[6:7] sc0

; __device__ __forceinline__ unsigned xb_ld(unsigned* p)              { return __hip_atomic_load(p, __ATOMIC_RELAXED, __HIP_MEMORY_SCOPE_AGENT); }
; __device__ __forceinline__ unsigned xb_add(unsigned* p, unsigned v) { return __hip_atomic_fetch_add(p, v, __ATOMIC_RELAXED, __HIP_MEMORY_SCOPE_AGENT); }
; #define XB_SPIN(cond, bar) do { unsigned _sp = 0; while (cond) { __builtin_amdgcn_s_sleep(1); \
;     if ((++_sp & 255u) == 0u) { if (xb_ld(&(bar)[XB_TMO])) break; if (_sp > XB_SPIN_CAP) { atomicAdd(&(bar)[XB_TMO], 1u); break; } } } } while (0)
; __device__ __forceinline__ void xcd_barrier(const XcdBarrier& b) {
;     ...
;             if (og + 1u == (tg + 1u) * nx) xb_add(&bar[XB_TOPGEN], 1u);
;             else XB_SPIN(xb_ld(&bar[XB_TOPGEN]) == tg, bar);
;             __builtin_amdgcn_fence(__ATOMIC_ACQUIRE, "agent");
;             xb_add(&bar[XB_XGEN(b.x)], 1u);
.LBB0_2109:
	s_or_b64 exec, exec, s[6:7]
	s_mov_b64 s[6:7], exec
	v_mbcnt_lo_u32_b32 v1, s6, 0
	v_mbcnt_hi_u32_b32 v1, s7, v1
	v_cmp_eq_u32_e32 vcc, 0, v1
	s_waitcnt vmcnt(0)
	s_nop 0
	s_and_saveexec_b64 s[8:9], vcc
	s_cbranch_execz .LBB0_2111
	s_bcnt1_i32_b64 s3, s[6:7]
	v_mov_b32_e32 v1, s3
	v_mov_b32_e32 v2, 0x2000
	global_atomic_add v2, v1, s[4:5] offset:1024

; __device__ __forceinline__ unsigned xb_ld(unsigned* p)              { return __hip_atomic_load(p, __ATOMIC_RELAXED, __HIP_MEMORY_SCOPE_AGENT); }
; __device__ __forceinline__ unsigned xb_add(unsigned* p, unsigned v) { return __hip_atomic_fetch_add(p, v, __ATOMIC_RELAXED, __HIP_MEMORY_SCOPE_AGENT); }
; #define XB_SPIN(cond, bar) do { unsigned _sp = 0; while (cond) { __builtin_amdgcn_s_sleep(1); \
;     if ((++_sp & 255u) == 0u) { if (xb_ld(&(bar)[XB_TMO])) break; if (_sp > XB_SPIN_CAP) { atomicAdd(&(bar)[XB_TMO], 1u); break; } } } } while (0)
; __device__ __forceinline__ void xcd_barrier(const XcdBarrier& b) {
;     ...
;         const unsigned old = xb_add(&bar[XB_XSUB(b.x)], 1u);
;         const unsigned gen = old / nloc;
;         if (old + 1u == (gen + 1u) * nloc) {
;             __builtin_amdgcn_fence(__ATOMIC_RELEASE, "agent");
;             asm volatile("s_waitcnt vmcnt(0)" ::: "memory");
;             const unsigned og = xb_add(&bar[XB_TOP], 1u);
;             const unsigned tg = og / nx;
;             if (og + 1u == (tg + 1u) * nx) xb_add(&bar[XB_TOPGEN], 1u);
;             else XB_SPIN(xb_ld(&bar[XB_TOPGEN]) == tg, bar);
;             __builtin_amdgcn_fence(__ATOMIC_ACQUIRE, "agent");
;             xb_add(&bar[XB_XGEN(b.x)], 1u);
;             asm volatile("s_waitcnt vmcnt(0)" ::: "memory");
;         } else {
;             XB_SPIN(xb_ld(&bar[XB_XGEN(b.x)]) == gen, bar);
.LBB0_2180:
	s_or_b64 exec, exec, s[10:11]
	v_cvt_f32_u32_e32 v5, v3
	s_waitcnt vmcnt(0)
	v_readfirstlane_b32 s3, v4
	v_sub_u32_e32 v4, 0, v3
	v_rcp_iflag_f32_e32 v5, v5
	v_add_u32_e32 v6, s3, v1
	v_mul_f32_e32 v5, 0x4f7ffffe, v5
	v_cvt_u32_f32_e32 v5, v5
	v_mul_lo_u32 v1, v4, v5
	v_mul_hi_u32 v1, v5, v1
	v_add_u32_e32 v1, v5, v1
	v_mul_hi_u32 v1, v6, v1
	v_mul_lo_u32 v4, v1, v3
	v_sub_u32_e32 v4, v6, v4
	v_add_u32_e32 v5, 1, v1
	v_cmp_ge_u32_e32 vcc, v4, v3
	s_nop 1
	v_cndmask_b32_e32 v1, v1, v5, vcc
	v_sub_u32_e32 v5, v4, v3
	v_cndmask_b32_e32 v4, v4, v5, vcc
	v_add_u32_e32 v5, 1, v1
	v_cmp_ge_u32_e32 vcc, v4, v3
	v_add_u32_e32 v4, 1, v6
	s_nop 0
	v_cndmask_b32_e32 v1, v1, v5, vcc
	v_mul_lo_u32 v5, v3, v1
	v_add_u32_e32 v3, v5, v3
	v_cmp_ne_u32_e32 vcc, v4, v3
	s_and_saveexec_b64 s[4:5], vcc
	s_xor_b64 s[8:9], exec, s[4:5]
	s_cbranch_execz .LBB0_2194
	s_waitcnt lgkmcnt(0)
	buffer_inv sc1
	v_mov_b32_e32 v2, 0x2000
	global_load_dword v2, v2, s[6:7] offset:1024 sc1
	s_add_u32 s12, s6, 0x2400
	s_addc_u32 s13, s7, 0
	s_waitcnt vmcnt(0)
	v_cmp_eq_u32_e32 vcc, v2, v1
	s_and_saveexec_b64 s[10:11], vcc
	s_cbranch_execz .LBB0_2193
	s_mov_b32 s3, 1
	s_mov_b64 s[14:15], 0
	s_branch .LBB0_2184

; __device__ __forceinline__ unsigned xb_add(unsigned* p, unsigned v) { return __hip_atomic_fetch_add(p, v, __ATOMIC_RELAXED, __HIP_MEMORY_SCOPE_AGENT); }
; __device__ __forceinline__ void xcd_barrier(const XcdBarrier& b) {
;     ...
;         if (old + 1u == (gen + 1u) * nloc) {
;             __builtin_amdgcn_fence(__ATOMIC_RELEASE, "agent");
;             asm volatile("s_waitcnt vmcnt(0)" ::: "memory");
;             const unsigned og = xb_add(&bar[XB_TOP], 1u);
.LBB0_2194:
	s_andn2_saveexec_b64 s[4:5], s[8:9]
	s_cbranch_execz .LBB0_2214
	s_mov_b64 s[8:9], exec
	buffer_wbl2 sc1
	s_waitcnt lgkmcnt(0)
	s_waitcnt vmcnt(0)
	buffer_inv sc1
	v_mbcnt_lo_u32_b32 v1, s8, 0
	v_mbcnt_hi_u32_b32 v1, s9, v1
	v_cmp_eq_u32_e32 vcc, 0, v1
	s_and_saveexec_b64 s[10:11], vcc
	s_cbranch_execz .LBB0_2197
	s_bcnt1_i32_b64 s3, s[8:9]
	v_readlane_b32 s4, v254, 29
	v_mov_b32_e32 v3, s3
	v_readlane_b32 s5, v254, 30
	s_nop 4
	global_atomic_add v3, v0, v3, s[4:5] sc0

; __device__ __forceinline__ unsigned xb_ld(unsigned* p)              { return __hip_atomic_load(p, __ATOMIC_RELAXED, __HIP_MEMORY_SCOPE_AGENT); }
; __device__ __forceinline__ unsigned xb_add(unsigned* p, unsigned v) { return __hip_atomic_fetch_add(p, v, __ATOMIC_RELAXED, __HIP_MEMORY_SCOPE_AGENT); }
; #define XB_SPIN(cond, bar) do { unsigned _sp = 0; while (cond) { __builtin_amdgcn_s_sleep(1); \
;     if ((++_sp & 255u) == 0u) { if (xb_ld(&(bar)[XB_TMO])) break; if (_sp > XB_SPIN_CAP) { atomicAdd(&(bar)[XB_TMO], 1u); break; } } } } while (0)
; __device__ __forceinline__ void xcd_barrier(const XcdBarrier& b) {
;     ...
;             if (og + 1u == (tg + 1u) * nx) xb_add(&bar[XB_TOPGEN], 1u);
;             else XB_SPIN(xb_ld(&bar[XB_TOPGEN]) == tg, bar);
;             __builtin_amdgcn_fence(__ATOMIC_ACQUIRE, "agent");
;             xb_add(&bar[XB_XGEN(b.x)], 1u);
.LBB0_2211:
	s_or_b64 exec, exec, s[8:9]
	s_mov_b64 s[8:9], exec
	v_mbcnt_lo_u32_b32 v1, s8, 0
	v_mbcnt_hi_u32_b32 v1, s9, v1
	v_cmp_eq_u32_e32 vcc, 0, v1
	s_waitcnt vmcnt(0)
	s_nop 0
	s_and_saveexec_b64 s[10:11], vcc
	s_cbranch_execz .LBB0_2213
	s_bcnt1_i32_b64 s3, s[8:9]
	v_mov_b32_e32 v1, s3
	v_mov_b32_e32 v2, 0x2000
	global_atomic_add v2, v1, s[6:7] offset:1024

; __device__ __forceinline__ unsigned xb_add(unsigned* p, unsigned v) { return __hip_atomic_fetch_add(p, v, __ATOMIC_RELAXED, __HIP_MEMORY_SCOPE_AGENT); }
; __device__ __forceinline__ void xcd_barrier(const XcdBarrier& b) {
;     ...
;         if (old + 1u == (gen + 1u) * nloc) {
;             __builtin_amdgcn_fence(__ATOMIC_RELEASE, "agent");
;             asm volatile("s_waitcnt vmcnt(0)" ::: "memory");
;             const unsigned og = xb_add(&bar[XB_TOP], 1u);
.LBB0_2417:
	s_mov_b64 s[6:7], exec
	buffer_wbl2 sc1
	s_waitcnt lgkmcnt(0)
	s_waitcnt vmcnt(0)
	buffer_inv sc1
	v_mbcnt_lo_u32_b32 v1, s6, 0
	v_mbcnt_hi_u32_b32 v1, s7, v1
	v_cmp_eq_u32_e32 vcc, 0, v1
	s_and_saveexec_b64 s[8:9], vcc
	s_cbranch_execz .LBB0_2419
	s_bcnt1_i32_b64 s3, s[6:7]
	v_readlane_b32 s6, v254, 29
	v_mov_b32_e32 v3, s3
	v_readlane_b32 s7, v254, 30
	s_nop 4
	global_atomic_add v3, v0, v3, s[6:7] sc0

; __device__ __forceinline__ unsigned xb_ld(unsigned* p)              { return __hip_atomic_load(p, __ATOMIC_RELAXED, __HIP_MEMORY_SCOPE_AGENT); }
; __device__ __forceinline__ unsigned xb_add(unsigned* p, unsigned v) { return __hip_atomic_fetch_add(p, v, __ATOMIC_RELAXED, __HIP_MEMORY_SCOPE_AGENT); }
; #define XB_SPIN(cond, bar) do { unsigned _sp = 0; while (cond) { __builtin_amdgcn_s_sleep(1); \
;     if ((++_sp & 255u) == 0u) { if (xb_ld(&(bar)[XB_TMO])) break; if (_sp > XB_SPIN_CAP) { atomicAdd(&(bar)[XB_TMO], 1u); break; } } } } while (0)
; __device__ __forceinline__ void xcd_barrier(const XcdBarrier& b) {
;     ...
;             if (og + 1u == (tg + 1u) * nx) xb_add(&bar[XB_TOPGEN], 1u);
;             else XB_SPIN(xb_ld(&bar[XB_TOPGEN]) == tg, bar);
;             __builtin_amdgcn_fence(__ATOMIC_ACQUIRE, "agent");
;             xb_add(&bar[XB_XGEN(b.x)], 1u);
.LBB0_2433:
	s_or_b64 exec, exec, s[6:7]
	s_mov_b64 s[6:7], exec
	v_mbcnt_lo_u32_b32 v1, s6, 0
	v_mbcnt_hi_u32_b32 v1, s7, v1
	v_cmp_eq_u32_e32 vcc, 0, v1
	s_waitcnt vmcnt(0)
	s_nop 0
	s_and_saveexec_b64 s[8:9], vcc
	s_cbranch_execnz .LBB0_2434
	s_getpc_b64 s[98:99]
